# P5 row-norm loop software-pipelined: next row loads one row ahead, no wait on the previous row stores
# baseline (speedup 1.0000x reference)
.LBB0_439:
	s_ashr_i32 s9, s8, 31
	s_lshl_b64 s[12:13], s[8:9], 7
	s_add_u32 s15, s12, 0x1800000
	s_addc_u32 s16, s13, 0
	s_lshl_b64 s[12:13], s[8:9], 16
	s_lshl_b32 s9, s14, 3
	s_add_i32 s9, s9, s71
	s_lshr_b32 s9, s9, 8
	s_mul_i32 s18, s9, 0xc00
	s_ashr_i32 s19, s18, 31
	s_lshl_b64 s[18:19], s[18:19], 2
	v_readlane_b32 s20, v245, 49
	v_readlane_b32 s21, v245, 50
	s_add_u32 s18, s20, s18
	s_addc_u32 s19, s21, s19
	s_add_u32 s20, s18, 0x1000
	s_addc_u32 s21, s19, 0
	s_nop 0
	global_load_dwordx4 v[22:25], v64, s[20:21]
	global_load_dwordx4 v[26:29], v65, s[20:21]
	global_load_dwordx4 v[30:33], v66, s[20:21]
	global_load_dwordx4 v[34:37], v67, s[20:21]
	global_load_dwordx4 v[38:41], v[18:19], off
	global_load_dwordx4 v[42:45], v[18:19], off offset:1024
	global_load_dwordx4 v[46:49], v[18:19], off offset:2048
	global_load_dwordx4 v[50:53], v[18:19], off offset:3072
	global_load_dwordx4 v[0:3], v64, s[18:19]
	global_load_dwordx4 v[4:7], v64, s[18:19] offset:1024
	global_load_dwordx4 v[8:11], v64, s[18:19] offset:2048
	global_load_dwordx4 v[12:15], v64, s[18:19] offset:3072
	v_mov_b32_e32 v21, s13
	v_or_b32_e32 v20, s12, v16
	v_lshl_add_u64 v[108:109], s[86:87], 0, v[20:21]
	v_add_co_u32_e32 v108, vcc, 0x2a000000, v108
	s_nop 1
	v_addc_co_u32_e32 v109, vcc, 0, v109, vcc
	global_load_dwordx2 v[100:101], v[108:109], off
	global_load_dwordx2 v[102:103], v[108:109], off offset:512
	global_load_dwordx2 v[104:105], v[108:109], off offset:1024
	global_load_dwordx2 v[106:107], v[108:109], off offset:1536
	v_lshl_add_u64 v[108:109], v[108:109], 0, s[10:11]
	s_mov_b32 s9, 32
	s_waitcnt vmcnt(15)
	v_pk_add_f32 v[24:25], v[24:25], 1.0 op_sel_hi:[1,0]
	v_pk_add_f32 v[54:55], v[22:23], 1.0 op_sel_hi:[1,0]
	s_waitcnt vmcnt(14)
	v_pk_add_f32 v[28:29], v[28:29], 1.0 op_sel_hi:[1,0]
	v_pk_add_f32 v[56:57], v[26:27], 1.0 op_sel_hi:[1,0]
	s_waitcnt vmcnt(13)
	v_pk_add_f32 v[32:33], v[32:33], 1.0 op_sel_hi:[1,0]
	v_pk_add_f32 v[70:71], v[30:31], 1.0 op_sel_hi:[1,0]
	s_waitcnt vmcnt(12)
	v_pk_add_f32 v[36:37], v[36:37], 1.0 op_sel_hi:[1,0]
	v_pk_add_f32 v[72:73], v[34:35], 1.0 op_sel_hi:[1,0]
	s_waitcnt vmcnt(11)
	v_pk_mul_f32 v[22:23], v[40:41], v[24:25]
	v_pk_mul_f32 v[24:25], v[38:39], v[54:55]
	s_waitcnt vmcnt(10)
	v_pk_mul_f32 v[26:27], v[44:45], v[28:29]
	v_pk_mul_f32 v[28:29], v[42:43], v[56:57]
	s_waitcnt vmcnt(9)
	v_pk_mul_f32 v[30:31], v[48:49], v[32:33]
	v_pk_mul_f32 v[32:33], v[46:47], v[70:71]
	s_waitcnt vmcnt(8)
	v_pk_mul_f32 v[34:35], v[52:53], v[36:37]
	v_pk_mul_f32 v[36:37], v[50:51], v[72:73]
	s_waitcnt vmcnt(0)
	s_branch .LBB0_441

.LBB0_441:
	v_lshl_add_u64 v[38:39], s[86:87], 0, v[20:21]
	s_waitcnt vmcnt(5)
	v_mov_b64_e32 v[42:43], v[100:101]
	v_mov_b64_e32 v[44:45], v[102:103]
	v_mov_b64_e32 v[48:49], v[104:105]
	v_mov_b64_e32 v[40:41], v[106:107]
	s_cmp_eq_u32 s9, 1
	s_cbranch_scc1 .Lp5_nopf
	global_load_dwordx2 v[100:101], v[108:109], off
	global_load_dwordx2 v[102:103], v[108:109], off offset:512
	global_load_dwordx2 v[104:105], v[108:109], off offset:1024
	global_load_dwordx2 v[106:107], v[108:109], off offset:1536
	v_lshl_add_u64 v[108:109], v[108:109], 0, s[10:11]
.Lp5_nopf:
	v_and_b32_e32 v55, 0xffff0000, v42
	v_and_b32_e32 v57, 0xffff0000, v43
	v_lshlrev_b32_e32 v54, 16, v42
	v_lshlrev_b32_e32 v56, 16, v43
	v_lshlrev_b32_e32 v53, 16, v45
	v_lshlrev_b32_e32 v52, 16, v44
	v_and_b32_e32 v51, 0xffff0000, v45
	v_and_b32_e32 v50, 0xffff0000, v44
	v_and_b32_e32 v47, 0xffff0000, v48
	v_lshlrev_b32_e32 v45, 16, v40
	v_and_b32_e32 v43, 0xffff0000, v40
	v_mul_f32_e32 v42, v57, v57
	v_mul_f32_e32 v44, v55, v55
	v_lshlrev_b32_e32 v46, 16, v48
	v_lshlrev_b32_e32 v48, 16, v49
	v_and_b32_e32 v49, 0xffff0000, v49
	v_pk_mul_f32 v[70:71], v[50:51], v[50:51]
	v_mov_b32_e32 v73, v45
	v_mul_f32_e32 v72, v47, v47
	v_pk_fma_f32 v[76:77], v[56:57], v[56:57], v[42:43] op_sel_hi:[1,1,0]
	v_pk_fma_f32 v[78:79], v[54:55], v[54:55], v[44:45] op_sel_hi:[1,1,0]
	v_lshlrev_b32_e32 v40, 16, v41
	v_and_b32_e32 v41, 0xffff0000, v41
	v_mul_f32_e32 v74, v49, v49
	v_pk_fma_f32 v[70:71], v[52:53], v[52:53], v[70:71]
	v_pk_fma_f32 v[80:81], v[46:47], v[46:47], v[72:73] op_sel_hi:[1,1,0]
	v_mov_b32_e32 v44, v78
	v_mov_b32_e32 v72, v76
	v_mul_f32_e32 v69, v43, v43
	v_mul_f32_e32 v82, v40, v40
	v_mul_f32_e32 v83, v41, v41
	v_pk_fma_f32 v[74:75], v[48:49], v[48:49], v[74:75] op_sel_hi:[1,1,0]
	v_pk_add_f32 v[76:77], v[78:79], v[76:77]
	v_pk_add_f32 v[70:71], v[70:71], v[70:71] op_sel:[0,1] op_sel_hi:[1,0]
	v_pk_mul_f32 v[72:73], v[44:45], v[72:73]
	v_mov_b32_e32 v81, v82
	v_mov_b32_e32 v75, v83
	v_mov_b32_e32 v71, v69
	v_mov_b32_e32 v77, v73
	v_pk_add_f32 v[74:75], v[80:81], v[74:75]
	v_pk_add_f32 v[70:71], v[76:77], v[70:71]
	s_nop 0
	v_pk_add_f32 v[70:71], v[70:71], v[74:75]
	s_nop 0
	v_add_f32_e32 v42, v70, v71
	ds_bpermute_b32 v44, v58, v42
	s_waitcnt lgkmcnt(0)
	v_add_f32_e32 v42, v42, v44
	ds_bpermute_b32 v44, v59, v42
	s_waitcnt lgkmcnt(0)
	v_add_f32_e32 v42, v42, v44
	ds_bpermute_b32 v44, v60, v42
	s_waitcnt lgkmcnt(0)
	v_add_f32_e32 v42, v42, v44
	ds_bpermute_b32 v44, v61, v42
	s_waitcnt lgkmcnt(0)
	v_add_f32_e32 v42, v42, v44
	ds_bpermute_b32 v44, v62, v42
	s_waitcnt lgkmcnt(0)
	v_add_f32_e32 v42, v42, v44
	ds_bpermute_b32 v44, v63, v42
	s_waitcnt lgkmcnt(0)
	v_add_f32_e32 v42, v42, v44
	v_fmamk_f32 v42, v42, 0x3a800000, v68
	v_mul_f32_e32 v44, 0x4b800000, v42
	v_cmp_gt_f32_e32 vcc, s2, v42
	s_nop 1
	v_cndmask_b32_e32 v42, v42, v44, vcc
	v_rsq_f32_e32 v42, v42
	s_nop 0
	v_mul_f32_e32 v44, 0x45800000, v42
	v_cndmask_b32_e32 v44, v42, v44, vcc
	s_and_saveexec_b64 s[12:13], s[0:1]
	s_cbranch_execz .LBB0_440
	s_add_u32 s18, s86, s15
	s_addc_u32 s19, s87, s16
	global_store_dword v17, v44, s[18:19]
	s_branch .LBB0_440
